# attention loop K/V LDS-DMA with scalar running bases + 32-bit lane offsets (no per-tile VALU address work)
# baseline (speedup 1.0000x reference)
.LBB0_65:
	s_nop 8
	v_max_f32_e32 v4, v17, v17
	v_max_f32_e32 v5, v33, v33
	v_max_f32_e32 v4, v5, v4
	v_max_f32_e32 v5, v18, v18
	v_max_f32_e32 v6, v34, v34
	v_max_f32_e32 v5, v6, v5
	v_max_f32_e32 v6, v19, v19
	v_max_f32_e32 v7, v35, v35
	v_max3_f32 v4, v32, v16, v4
	v_max_f32_e32 v6, v7, v6
	v_max3_f32 v4, v4, v5, v6
	v_max_f32_e32 v5, v20, v20
	v_max_f32_e32 v6, v36, v36
	v_max_f32_e32 v5, v6, v5
	v_max_f32_e32 v6, v21, v21
	v_max_f32_e32 v7, v37, v37
	v_max_f32_e32 v6, v7, v6
	v_max3_f32 v4, v4, v5, v6
	v_max_f32_e32 v5, v22, v22
	v_max_f32_e32 v6, v38, v38
	v_max_f32_e32 v5, v6, v5
	v_max_f32_e32 v6, v23, v23
	v_max_f32_e32 v7, v39, v39
	v_max_f32_e32 v6, v7, v6
	v_max3_f32 v4, v4, v5, v6
	v_max_f32_e32 v5, v24, v24
	v_max_f32_e32 v6, v40, v40
	v_max_f32_e32 v5, v6, v5
	v_max_f32_e32 v6, v25, v25
	v_max_f32_e32 v7, v41, v41
	v_max_f32_e32 v6, v7, v6
	v_max3_f32 v4, v4, v5, v6
	v_max_f32_e32 v5, v26, v26
	v_max_f32_e32 v6, v42, v42
	v_max_f32_e32 v5, v6, v5
	v_max_f32_e32 v6, v27, v27
	v_max_f32_e32 v7, v43, v43
	v_max_f32_e32 v6, v7, v6
	v_max3_f32 v4, v4, v5, v6
	v_max_f32_e32 v5, v28, v28
	v_max_f32_e32 v6, v44, v44
	v_max_f32_e32 v5, v6, v5
	v_max_f32_e32 v6, v29, v29
	v_max_f32_e32 v7, v45, v45
	v_max_f32_e32 v6, v7, v6
	v_max3_f32 v4, v4, v5, v6
	v_max_f32_e32 v5, v30, v30
	v_max_f32_e32 v6, v46, v46
	v_max_f32_e32 v5, v6, v5
	v_max_f32_e32 v6, v31, v31
	v_max_f32_e32 v7, v47, v47
	v_max_f32_e32 v6, v7, v6
	v_max3_f32 v4, v4, v5, v6
	v_and_b32_e32 v6, 64, v227
	v_xor_b32_e32 v5, 32, v227
	v_add_u32_e32 v6, 64, v6
	v_cmp_lt_i32_e32 vcc, v5, v6
	v_bfe_u32 v1, v48, 2, 2
	v_lshlrev_b32_e32 v0, 3, v48
	v_cndmask_b32_e32 v5, v227, v5, vcc
	v_lshlrev_b32_e32 v129, 2, v5
	ds_bpermute_b32 v5, v129, v4
	v_or_b32_e32 v2, v127, v1
	v_lshlrev_b32_e32 v3, 1, v48
	v_lshlrev_b32_e32 v2, 8, v2
	v_and_b32_e32 v3, 32, v3
	v_and_b32_e32 v0, 24, v0
	v_or3_b32 v138, v0, v3, v2
	s_waitcnt lgkmcnt(0)
	v_max_f32_e32 v0, v5, v5
	v_max_f32_e32 v48, v4, v0
	v_sub_f32_e32 v32, v32, v48
	v_sub_f32_e32 v16, v16, v48
	v_exp_f32_e32 v50, v32
	v_exp_f32_e32 v51, v16
	v_sub_f32_e32 v16, v33, v48
	v_sub_f32_e32 v17, v17, v48
	v_exp_f32_e32 v16, v16
	v_exp_f32_e32 v17, v17
	v_sub_f32_e32 v32, v34, v48
	v_sub_f32_e32 v18, v18, v48
	v_exp_f32_e32 v32, v32
	v_exp_f32_e32 v33, v18
	v_sub_f32_e32 v18, v35, v48
	v_sub_f32_e32 v19, v19, v48
	v_exp_f32_e32 v18, v18
	v_exp_f32_e32 v19, v19
	v_sub_f32_e32 v36, v36, v48
	v_sub_f32_e32 v20, v20, v48
	v_pk_add_f32 v[34:35], v[50:51], 0 op_sel_hi:[1,0]
	v_exp_f32_e32 v52, v36
	v_exp_f32_e32 v53, v20
	v_sub_f32_e32 v20, v37, v48
	v_sub_f32_e32 v21, v21, v48
	v_pk_add_f32 v[34:35], v[16:17], v[34:35]
	v_exp_f32_e32 v20, v20
	v_exp_f32_e32 v21, v21
	v_sub_f32_e32 v36, v38, v48
	v_sub_f32_e32 v22, v22, v48
	v_pk_add_f32 v[34:35], v[32:33], v[34:35]
	v_exp_f32_e32 v36, v36
	v_exp_f32_e32 v37, v22
	v_sub_f32_e32 v22, v39, v48
	v_sub_f32_e32 v23, v23, v48
	v_pk_add_f32 v[34:35], v[18:19], v[34:35]
	v_exp_f32_e32 v22, v22
	v_exp_f32_e32 v23, v23
	v_sub_f32_e32 v38, v40, v48
	v_sub_f32_e32 v24, v24, v48
	v_pk_add_f32 v[34:35], v[52:53], v[34:35]
	v_exp_f32_e32 v38, v38
	v_exp_f32_e32 v39, v24
	v_sub_f32_e32 v24, v41, v48
	v_sub_f32_e32 v25, v25, v48
	v_pk_add_f32 v[34:35], v[20:21], v[34:35]
	v_exp_f32_e32 v24, v24
	v_exp_f32_e32 v25, v25
	v_sub_f32_e32 v40, v42, v48
	v_sub_f32_e32 v26, v26, v48
	v_pk_add_f32 v[34:35], v[36:37], v[34:35]
	v_exp_f32_e32 v40, v40
	v_exp_f32_e32 v41, v26
	v_sub_f32_e32 v26, v43, v48
	v_sub_f32_e32 v27, v27, v48
	v_pk_add_f32 v[34:35], v[22:23], v[34:35]
	v_exp_f32_e32 v26, v26
	v_exp_f32_e32 v27, v27
	v_sub_f32_e32 v42, v44, v48
	v_sub_f32_e32 v28, v28, v48
	v_pk_add_f32 v[34:35], v[38:39], v[34:35]
	v_exp_f32_e32 v42, v42
	v_exp_f32_e32 v43, v28
	v_sub_f32_e32 v28, v45, v48
	v_sub_f32_e32 v29, v29, v48
	v_pk_add_f32 v[34:35], v[24:25], v[34:35]
	v_exp_f32_e32 v28, v28
	v_exp_f32_e32 v29, v29
	v_sub_f32_e32 v44, v46, v48
	v_sub_f32_e32 v30, v30, v48
	v_pk_add_f32 v[34:35], v[40:41], v[34:35]
	v_exp_f32_e32 v44, v44
	v_exp_f32_e32 v45, v30
	v_sub_f32_e32 v30, v47, v48
	v_sub_f32_e32 v31, v31, v48
	v_pk_add_f32 v[34:35], v[26:27], v[34:35]
	v_exp_f32_e32 v30, v30
	v_exp_f32_e32 v31, v31
	v_exp_f32_e64 v0, -v48
	v_pk_add_f32 v[34:35], v[42:43], v[34:35]
	s_lshl_b32 s2, s14, 7
	v_pk_add_f32 v[34:35], v[28:29], v[34:35]
	v_mul_f32_e32 v0, 0, v0
	v_pk_add_f32 v[34:35], v[44:45], v[34:35]
	v_cvt_pk_bf16_f32 v220, v50, v16
	v_pk_add_f32 v[34:35], v[30:31], v[34:35]
	v_sub_u32_e32 v16, v127, v128
	v_pk_add_f32 v[34:35], v[34:35], v[34:35] op_sel_hi:[0,1]
	s_and_b64 s[0:1], s[0:1], exec
	v_mov_b32_e32 v14, v0
	v_mov_b32_e32 v15, v0
	s_waitcnt vmcnt(4) lgkmcnt(0)
	s_barrier
; __device__ __forceinline__ void attn_item(CP& P, int L, int sq, int hh, int qt, float lam, float lam_init, LAS unsigned char* lds) {
;     ...
;     const bf16_t* gk[2]; const bf16_t* gv[2];
; #pragma unroll
;     for (int i = 0; i < 2; ++i) { const int n = 2 * wid + i;
;         { const int rr = 8 * (n & 7) + (lane >> 3), c = (lane & 7) ^ ((rr >> 1) & 7); gk[i] = proj + (size_t)(sstart + rr) * PROJ_PITCH + KOFF + hh * 128 + (n >> 3) * 64 + c * 8; }
;         { const int rr = 4 * n + (lane >> 4), ch = (lane & 15) ^ (4 * (rr & 3)); gv[i] = proj + (size_t)(sstart + rr) * PROJ_PITCH + VOFF + hh * 128 + ch * 8; } }
;     ...
;     for (int t = 0; t < ntiles; ++t) {
;         { const int tn = (t + 2 < ntiles) ? t + 2 : ntiles - 1; ATT_DMA(tn, (t + 2) & 3); }
;         const int k0_ = t * 64; const bool farR_ = (k0_ - (q0w + 31) >= 128), farL_ = (q0w - (k0_ + 63) >= 128); far_ = farR_ || farL_;
;         const float cinit_ = (far_ ? (farR_ ? tbl[256] : tbl[0]) : 0.f) - mref;
	v_mov_b32_e32 v49, v0
	v_mov_b32_e32 v34, v193
	v_subrev_u32_e32 v16, s10, v16
	s_cselect_b32 s15, 32, 64
	v_lshlrev_b32_e32 v139, 6, v1
	v_mov_b32_e32 v1, v0
	v_mov_b32_e32 v2, v0
	v_mov_b32_e32 v3, v0
	v_mov_b32_e32 v4, v0
	v_mov_b32_e32 v5, v0
	v_mov_b32_e32 v6, v0
	v_mov_b32_e32 v7, v0
	v_mov_b32_e32 v8, v0
	v_mov_b32_e32 v9, v0
	v_mov_b32_e32 v10, v0
	v_mov_b32_e32 v11, v0
	v_mov_b32_e32 v12, v0
	v_mov_b32_e32 v13, v0
	v_pk_add_f32 v[124:125], v[48:49], v[34:35]
	v_cvt_pk_bf16_f32 v208, v39, v25
	v_cvt_pk_bf16_f32 v209, v41, v27
	v_cvt_pk_bf16_f32 v210, v43, v29
	v_cvt_pk_bf16_f32 v211, v45, v31
	v_cvt_pk_bf16_f32 v212, v51, v17
	v_cvt_pk_bf16_f32 v213, v33, v19
	v_cvt_pk_bf16_f32 v214, v53, v21
	v_cvt_pk_bf16_f32 v215, v37, v23
	v_cvt_pk_bf16_f32 v216, v38, v24
	v_cvt_pk_bf16_f32 v217, v40, v26
	v_cvt_pk_bf16_f32 v218, v42, v28
	v_cvt_pk_bf16_f32 v219, v44, v30
	v_cvt_pk_bf16_f32 v221, v32, v18
	v_cvt_pk_bf16_f32 v222, v52, v20
	v_cvt_pk_bf16_f32 v223, v36, v22
	v_subrev_u32_e32 v141, s20, v16
	v_mov_b64_e32 v[62:63], v[14:15]
	v_mov_b64_e32 v[46:47], v[14:15]
	v_mov_b64_e32 v[30:31], v[14:15]
	v_ashrrev_i32_e32 v115, 31, v114
	s_mov_b32 s14, 64
	s_mov_b32 s16, 1
	s_add_i32 s17, s15, -1
	v_add_u32_e32 v140, 0, v138
	v_xor_b32_e32 v137, 64, v139
	v_xor_b32_e32 v136, 0x80, v139
	v_xor_b32_e32 v135, 0xc0, v139
	s_add_i32 s18, s19, 0x9e
	s_addk_i32 s19, 0xff42
	s_mov_b32 s20, 0x20000
	v_mov_b64_e32 v[60:61], v[12:13]
	v_mov_b64_e32 v[58:59], v[10:11]
	v_mov_b64_e32 v[56:57], v[8:9]
	v_mov_b64_e32 v[54:55], v[6:7]
	v_mov_b64_e32 v[52:53], v[4:5]
	v_mov_b64_e32 v[50:51], v[2:3]
	v_mov_b64_e32 v[48:49], v[0:1]
	v_mov_b64_e32 v[44:45], v[12:13]
	v_mov_b64_e32 v[42:43], v[10:11]
	v_mov_b64_e32 v[40:41], v[8:9]
	v_mov_b64_e32 v[38:39], v[6:7]
	v_mov_b64_e32 v[36:37], v[4:5]
	v_mov_b64_e32 v[34:35], v[2:3]
	v_mov_b64_e32 v[32:33], v[0:1]
	v_mov_b64_e32 v[28:29], v[12:13]
	v_mov_b64_e32 v[26:27], v[10:11]
	v_mov_b64_e32 v[24:25], v[8:9]
	v_mov_b64_e32 v[22:23], v[6:7]
	v_mov_b64_e32 v[20:21], v[4:5]
	v_mov_b64_e32 v[18:19], v[2:3]
	v_mov_b64_e32 v[16:17], v[0:1]
	v_readfirstlane_b32 s22, v116
	v_readfirstlane_b32 s23, v117
	v_readfirstlane_b32 s24, v118
	v_readfirstlane_b32 s25, v119
	v_readfirstlane_b32 s36, v120
	v_readfirstlane_b32 s37, v121
	v_readfirstlane_b32 s38, v122
	v_readfirstlane_b32 s39, v123
	s_nop 3
	s_sub_u32 s22, s22, 0x80000000
	s_subb_u32 s23, s23, 0
	s_sub_u32 s24, s24, 0x80000000
	s_subb_u32 s25, s25, 0
	s_sub_u32 s36, s36, 0x80000000
	s_subb_u32 s37, s37, 0
	s_sub_u32 s38, s38, 0x80000000
	s_subb_u32 s39, s39, 0
	v_subrev_u32_e32 v116, s22, v116
	v_subrev_u32_e32 v118, s24, v118
	v_subrev_u32_e32 v120, s36, v120
	v_subrev_u32_e32 v122, s38, v122
	s_add_u32 s22, s22, 0x210000
	s_addc_u32 s23, s23, 0
	s_add_u32 s24, s24, 0x210000
	s_addc_u32 s25, s25, 0
	s_add_u32 s36, s36, 0x210000
	s_addc_u32 s37, s37, 0
	s_add_u32 s38, s38, 0x210000
	s_addc_u32 s39, s39, 0
	s_branch .LBB0_67
.LBB0_67:
	s_add_i32 s0, s16, 2
	s_cmp_lt_i32 s0, s17
	s_cselect_b32 s4, 0xb0000, 0
	s_add_i32 s0, s20, 0xffff8000
	s_and_b32 s0, s0, 0x18000
	s_add_i32 s5, s11, s0
	s_add_i32 s21, s5, 0x4000
	s_mov_b32 m0, s5
	s_nop 0
	global_load_lds_dwordx4 v116, s[22:23]
	s_mov_b32 m0, s21
	s_nop 0
	global_load_lds_dwordx4 v118, s[24:25]
	s_add_i32 m0, s5, 0x400
	s_nop 0
	global_load_lds_dwordx4 v120, s[36:37]
	s_add_i32 m0, s5, 0x4400
	s_nop 0
	global_load_lds_dwordx4 v122, s[38:39]
	s_add_u32 s22, s22, s4
	s_addc_u32 s23, s23, 0
	s_add_u32 s24, s24, s4
	s_addc_u32 s25, s25, 0
	s_add_u32 s36, s36, s4
	s_addc_u32 s37, s37, 0
	s_add_u32 s38, s38, s4
	s_addc_u32 s39, s39, 0
	s_cmp_le_u32 s14, s18
	s_cselect_b64 s[4:5], -1, 0
	s_cmp_ge_i32 s14, s19
	s_cselect_b64 s[0:1], -1, 0
	s_and_b64 s[0:1], s[4:5], s[0:1]
	s_and_b64 vcc, exec, s[0:1]
	v_mov_b32_e32 v64, 0
	s_cbranch_vccnz .LBB0_72
	s_and_b64 vcc, exec, s[4:5]
	s_cbranch_vccz .LBB0_70
	s_add_i32 s4, 0, 0x20000
	v_mov_b32_e32 v64, s4
	ds_read_b32 v64, v64
	s_cbranch_execz .LBB0_71
	s_branch .LBB0_72
